# P+2: odd workgroups run the merge loop before their ret_chunk items (streaming and LDS-bound work overlap across workgroups)
# speedup vs baseline: 1.0090x; 1.0090x over previous
.LBB0_433:
	s_andn2_b64 vcc, exec, s[0:1]
	s_cbranch_vccnz .LBB0_508
	s_mov_b32 s100, 0
.Lp2_again:
	s_mov_b64 s[0:1], 0
	s_add_u32 s46, s80, s0
	s_addc_u32 s47, s81, s1
	v_readlane_b32 s62, v254, 0
	v_mov_b32_e32 v149, v230
	s_cmpk_lt_i32 s62, 0x200
	s_cbranch_scc0 .LBB0_450
	s_cmp_lg_u32 s100, 0
	s_cbranch_scc1 .Lp2_chunk
	s_bitcmp1_b32 s62, 0
	s_cbranch_scc0 .Lp2_chunk
	s_mov_b32 s100, 1
	s_branch .LBB0_450
.Lp2_chunk:
	s_add_u32 s36, s46, 0x19c00000
	s_addc_u32 s37, s47, 0
	s_lshl_b32 s0, s28, 26
	s_add_u32 s0, s46, s0
	s_addc_u32 s1, s47, 0
	s_add_u32 s2, s0, 0x3c00000
	s_addc_u32 s3, s1, 0
	s_add_u32 s38, s46, 0x15c00000
	s_addc_u32 s39, s47, 0
	s_mov_b32 s63, s62
	s_branch .LBB0_437

.LBB0_450:
	s_cmp_eq_u32 s100, 2
	s_cbranch_scc1 .Lp2_done
	v_lshl_add_u32 v4, s62, 9, v149
	s_mov_b32 s10, 0x200000
	v_cmp_gt_i32_e32 vcc, s10, v4
	s_and_saveexec_b64 s[0:1], vcc
	v_readlane_b32 s8, v254, 11
	v_readlane_b32 s9, v254, 12
	s_cbranch_execz .LBB0_453
	s_add_u32 s2, s46, 0x11c00000
	s_addc_u32 s3, s47, 0
	s_add_u32 s36, s46, 0xbc00000
	s_addc_u32 s37, s47, 0
	s_add_u32 s38, s46, 0xdc00000
	s_addc_u32 s39, s47, 0
	s_add_u32 s40, s46, 0xfc00000
	s_addc_u32 s41, s47, 0
	s_add_u32 s46, s46, 0x13c00000
	v_lshlrev_b32_e32 v0, 3, v149
	s_addc_u32 s47, s47, 0
	v_lshl_add_u32 v5, s62, 12, v0
	s_mov_b64 s[62:63], 0
	s_add_u32 s14, s2, 0x100000
	s_addc_u32 s15, s3, 0
	s_add_u32 s16, s2, 0x200000
	s_addc_u32 s17, s3, 0
	v_add_u32_e32 v77, s8, v4
	s_mov_b32 s6, 0x1fffff
	v_lshrrev_b32_e32 v73, 6, v4
	v_bfe_u32 v74, v4, 3, 3
	v_and_b32_e32 v75, 7, v4
	v_lshlrev_b32_e32 v217, 5, v73
	v_lshl_or_b32 v217, v74, 2, v217
	v_lshlrev_b32_e32 v216, 10, v73
	v_lshl_or_b32 v216, v74, 7, v216
	v_lshl_or_b32 v216, v75, 4, v216
	global_load_dword v200, v217, s[2:3]
	global_load_dword v201, v217, s[14:15]
	global_load_dword v202, v217, s[16:17]
	global_load_dwordx4 v[204:207], v216, s[36:37]
	global_load_dwordx4 v[208:211], v216, s[38:39]
	global_load_dwordx4 v[212:215], v216, s[40:41]
	v_lshrrev_b32_e32 v73, 6, v77
	v_bfe_u32 v74, v77, 3, 3
	v_and_b32_e32 v75, 7, v77
	v_lshlrev_b32_e32 v197, 5, v73
	v_lshl_or_b32 v197, v74, 2, v197
	v_lshlrev_b32_e32 v196, 10, v73
	v_lshl_or_b32 v196, v74, 7, v196
	v_lshl_or_b32 v196, v75, 4, v196
	global_load_dword v220, v197, s[2:3]
	global_load_dword v221, v197, s[14:15]
	global_load_dword v222, v197, s[16:17]
	global_load_dwordx4 v[184:187], v196, s[36:37]
	global_load_dwordx4 v[188:191], v196, s[38:39]
	global_load_dwordx4 v[192:195], v196, s[40:41]
	s_waitcnt vmcnt(6)
.LBB0_452:
	v_max3_f32 v91, v200, v201, v202
	v_sub_f32_e32 v0, v200, v91
	v_cmp_gt_f32_e32 vcc, s97, v0
	s_nop 1
	v_cndmask_b32_e32 v2, 0, v233, vcc
	v_add_f32_e32 v0, v0, v2
	v_exp_f32_e32 v0, v0
	v_cndmask_b32_e32 v2, 0, v236, vcc
	v_ldexp_f32 v3, v0, v2
	v_sub_f32_e32 v0, v201, v91
	v_cmp_gt_f32_e32 vcc, s97, v0
	s_nop 1
	v_cndmask_b32_e32 v2, 0, v233, vcc
	v_add_f32_e32 v0, v0, v2
	v_exp_f32_e32 v0, v0
	v_cndmask_b32_e32 v2, 0, v236, vcc
	v_ldexp_f32 v2, v0, v2
	v_sub_f32_e32 v0, v202, v91
	v_cmp_gt_f32_e32 vcc, s97, v0
	s_nop 1
	v_cndmask_b32_e32 v88, 0, v233, vcc
	v_add_f32_e32 v0, v0, v88
	v_exp_f32_e32 v0, v0
	v_cndmask_b32_e32 v88, 0, v236, vcc
	v_ldexp_f32 v0, v0, v88
	v_add_f32_e32 v88, v3, v2
	v_add_f32_e32 v88, v0, v88
	v_div_scale_f32 v89, s[6:7], v88, v88, 1.0
	v_rcp_f32_e32 v91, v89
	s_mov_b32 s6, 0x1fffff
	v_fma_f32 v92, -v89, v91, 1.0
	v_fmac_f32_e32 v91, v92, v91
	v_div_scale_f32 v92, vcc, 1.0, v88, 1.0
	v_mul_f32_e32 v93, v92, v91
	v_fma_f32 v94, -v89, v93, v92
	v_fmac_f32_e32 v93, v94, v91
	v_fma_f32 v89, -v89, v93, v92
	v_div_fmas_f32 v89, v89, v91, v93
	v_div_fixup_f32 v98, v89, v88, 1.0
	v_pk_mul_f32 v[2:3], v[2:3], v[98:99] op_sel_hi:[1,0]
	v_mul_f32_e32 v0, v0, v98
	v_lshlrev_b32_e32 v102, 16, v204
	v_and_b32_e32 v99, 0xffff0000, v204
	v_and_b32_e32 v103, 0xffff0000, v208
	v_lshlrev_b32_e32 v98, 16, v208
	v_pk_mul_f32 v[102:103], v[2:3], v[102:103] op_sel:[1,0] op_sel_hi:[0,1]
	v_lshlrev_b32_e32 v104, 16, v212
	v_and_b32_e32 v105, 0xffff0000, v212
	v_pk_fma_f32 v[98:99], v[2:3], v[98:99], v[102:103]
	v_lshlrev_b32_e32 v90, 16, v205
	v_pk_fma_f32 v[98:99], v[0:1], v[104:105], v[98:99] op_sel_hi:[0,1,1]
	v_cvt_pk_bf16_f32 v86, v98, v99
	v_lshlrev_b32_e32 v98, 16, v209
	v_and_b32_e32 v91, 0xffff0000, v209
	v_and_b32_e32 v99, 0xffff0000, v205
	v_pk_mul_f32 v[90:91], v[2:3], v[90:91] op_sel:[1,0] op_sel_hi:[0,1]
	v_lshlrev_b32_e32 v94, 16, v213
	v_and_b32_e32 v95, 0xffff0000, v213
	v_pk_fma_f32 v[90:91], v[2:3], v[98:99], v[90:91]
	v_lshlrev_b32_e32 v98, 16, v214
	v_pk_fma_f32 v[90:91], v[0:1], v[94:95], v[90:91] op_sel_hi:[0,1,1]
	v_lshlrev_b32_e32 v94, 16, v206
	v_and_b32_e32 v95, 0xffff0000, v210
	v_cvt_pk_bf16_f32 v87, v90, v91
	v_lshlrev_b32_e32 v90, 16, v210
	v_and_b32_e32 v91, 0xffff0000, v206
	v_pk_mul_f32 v[94:95], v[2:3], v[94:95] op_sel:[1,0] op_sel_hi:[0,1]
	v_and_b32_e32 v99, 0xffff0000, v214
	v_pk_fma_f32 v[90:91], v[2:3], v[90:91], v[94:95]
	v_lshlrev_b32_e32 v92, 16, v207
	v_pk_fma_f32 v[90:91], v[0:1], v[98:99], v[90:91] op_sel_hi:[0,1,1]
	v_cvt_pk_bf16_f32 v88, v90, v91
	v_lshlrev_b32_e32 v90, 16, v211
	v_and_b32_e32 v93, 0xffff0000, v211
	v_and_b32_e32 v91, 0xffff0000, v207
	v_pk_mul_f32 v[92:93], v[2:3], v[92:93] op_sel:[1,0] op_sel_hi:[0,1]
	v_pk_fma_f32 v[2:3], v[2:3], v[90:91], v[92:93]
	v_lshlrev_b32_e32 v90, 16, v215
	v_and_b32_e32 v91, 0xffff0000, v215
	v_pk_fma_f32 v[2:3], v[0:1], v[90:91], v[2:3] op_sel_hi:[0,1,1]
	v_cvt_pk_bf16_f32 v89, v2, v3
	global_store_dwordx4 v216, v[86:89], s[46:47]
	v_lshl_add_u32 v4, s8, 1, v4
	v_cmp_lt_i32_e32 vcc, s6, v77
	v_lshrrev_b32_e32 v73, 6, v4
	v_bfe_u32 v74, v4, 3, 3
	v_and_b32_e32 v75, 7, v4
	v_lshlrev_b32_e32 v217, 5, v73
	v_lshl_or_b32 v217, v74, 2, v217
	v_lshlrev_b32_e32 v216, 10, v73
	v_lshl_or_b32 v216, v74, 7, v216
	v_lshl_or_b32 v216, v75, 4, v216
	global_load_dword v200, v217, s[2:3]
	global_load_dword v201, v217, s[14:15]
	global_load_dword v202, v217, s[16:17]
	global_load_dwordx4 v[204:207], v216, s[36:37]
	global_load_dwordx4 v[208:211], v216, s[38:39]
	global_load_dwordx4 v[212:215], v216, s[40:41]
	s_or_b64 s[62:63], vcc, s[62:63]
	s_andn2_b64 exec, exec, s[62:63]
	s_cbranch_execz .Lmerge_exit
	s_waitcnt vmcnt(7)
	v_max3_f32 v91, v220, v221, v222
	v_sub_f32_e32 v0, v220, v91
	v_cmp_gt_f32_e32 vcc, s97, v0
	s_nop 1
	v_cndmask_b32_e32 v2, 0, v233, vcc
	v_add_f32_e32 v0, v0, v2
	v_exp_f32_e32 v0, v0
	v_cndmask_b32_e32 v2, 0, v236, vcc
	v_ldexp_f32 v3, v0, v2
	v_sub_f32_e32 v0, v221, v91
	v_cmp_gt_f32_e32 vcc, s97, v0
	s_nop 1
	v_cndmask_b32_e32 v2, 0, v233, vcc
	v_add_f32_e32 v0, v0, v2
	v_exp_f32_e32 v0, v0
	v_cndmask_b32_e32 v2, 0, v236, vcc
	v_ldexp_f32 v2, v0, v2
	v_sub_f32_e32 v0, v222, v91
	v_cmp_gt_f32_e32 vcc, s97, v0
	s_nop 1
	v_cndmask_b32_e32 v88, 0, v233, vcc
	v_add_f32_e32 v0, v0, v88
	v_exp_f32_e32 v0, v0
	v_cndmask_b32_e32 v88, 0, v236, vcc
	v_ldexp_f32 v0, v0, v88
	v_add_f32_e32 v88, v3, v2
	v_add_f32_e32 v88, v0, v88
	v_div_scale_f32 v89, s[6:7], v88, v88, 1.0
	v_rcp_f32_e32 v91, v89
	s_mov_b32 s6, 0x1fffff
	v_fma_f32 v92, -v89, v91, 1.0
	v_fmac_f32_e32 v91, v92, v91
	v_div_scale_f32 v92, vcc, 1.0, v88, 1.0
	v_mul_f32_e32 v93, v92, v91
	v_fma_f32 v94, -v89, v93, v92
	v_fmac_f32_e32 v93, v94, v91
	v_fma_f32 v89, -v89, v93, v92
	v_div_fmas_f32 v89, v89, v91, v93
	v_div_fixup_f32 v98, v89, v88, 1.0
	v_pk_mul_f32 v[2:3], v[2:3], v[98:99] op_sel_hi:[1,0]
	v_mul_f32_e32 v0, v0, v98
	v_lshlrev_b32_e32 v102, 16, v184
	v_and_b32_e32 v99, 0xffff0000, v184
	v_and_b32_e32 v103, 0xffff0000, v188
	v_lshlrev_b32_e32 v98, 16, v188
	v_pk_mul_f32 v[102:103], v[2:3], v[102:103] op_sel:[1,0] op_sel_hi:[0,1]
	v_lshlrev_b32_e32 v104, 16, v192
	v_and_b32_e32 v105, 0xffff0000, v192
	v_pk_fma_f32 v[98:99], v[2:3], v[98:99], v[102:103]
	v_lshlrev_b32_e32 v90, 16, v185
	v_pk_fma_f32 v[98:99], v[0:1], v[104:105], v[98:99] op_sel_hi:[0,1,1]
	v_cvt_pk_bf16_f32 v86, v98, v99
	v_lshlrev_b32_e32 v98, 16, v189
	v_and_b32_e32 v91, 0xffff0000, v189
	v_and_b32_e32 v99, 0xffff0000, v185
	v_pk_mul_f32 v[90:91], v[2:3], v[90:91] op_sel:[1,0] op_sel_hi:[0,1]
	v_lshlrev_b32_e32 v94, 16, v193
	v_and_b32_e32 v95, 0xffff0000, v193
	v_pk_fma_f32 v[90:91], v[2:3], v[98:99], v[90:91]
	v_lshlrev_b32_e32 v98, 16, v194
	v_pk_fma_f32 v[90:91], v[0:1], v[94:95], v[90:91] op_sel_hi:[0,1,1]
	v_lshlrev_b32_e32 v94, 16, v186
	v_and_b32_e32 v95, 0xffff0000, v190
	v_cvt_pk_bf16_f32 v87, v90, v91
	v_lshlrev_b32_e32 v90, 16, v190
	v_and_b32_e32 v91, 0xffff0000, v186
	v_pk_mul_f32 v[94:95], v[2:3], v[94:95] op_sel:[1,0] op_sel_hi:[0,1]
	v_and_b32_e32 v99, 0xffff0000, v194
	v_pk_fma_f32 v[90:91], v[2:3], v[90:91], v[94:95]
	v_lshlrev_b32_e32 v92, 16, v187
	v_pk_fma_f32 v[90:91], v[0:1], v[98:99], v[90:91] op_sel_hi:[0,1,1]
	v_cvt_pk_bf16_f32 v88, v90, v91
	v_lshlrev_b32_e32 v90, 16, v191
	v_and_b32_e32 v93, 0xffff0000, v191
	v_and_b32_e32 v91, 0xffff0000, v187
	v_pk_mul_f32 v[92:93], v[2:3], v[92:93] op_sel:[1,0] op_sel_hi:[0,1]
	v_pk_fma_f32 v[2:3], v[2:3], v[90:91], v[92:93]
	v_lshlrev_b32_e32 v90, 16, v195
	v_and_b32_e32 v91, 0xffff0000, v195
	v_pk_fma_f32 v[2:3], v[0:1], v[90:91], v[2:3] op_sel_hi:[0,1,1]
	v_cvt_pk_bf16_f32 v89, v2, v3
	global_store_dwordx4 v196, v[86:89], s[46:47]
	v_lshl_add_u32 v77, s8, 1, v77
	v_cmp_lt_i32_e32 vcc, s6, v4
	v_lshrrev_b32_e32 v73, 6, v77
	v_bfe_u32 v74, v77, 3, 3
	v_and_b32_e32 v75, 7, v77
	v_lshlrev_b32_e32 v197, 5, v73
	v_lshl_or_b32 v197, v74, 2, v197
	v_lshlrev_b32_e32 v196, 10, v73
	v_lshl_or_b32 v196, v74, 7, v196
	v_lshl_or_b32 v196, v75, 4, v196
	global_load_dword v220, v197, s[2:3]
	global_load_dword v221, v197, s[14:15]
	global_load_dword v222, v197, s[16:17]
	global_load_dwordx4 v[184:187], v196, s[36:37]
	global_load_dwordx4 v[188:191], v196, s[38:39]
	global_load_dwordx4 v[192:195], v196, s[40:41]
	s_or_b64 s[62:63], vcc, s[62:63]
	s_waitcnt vmcnt(7)
	s_andn2_b64 exec, exec, s[62:63]
	s_cbranch_execnz .LBB0_452

.LBB0_453:
	s_or_b64 exec, exec, s[0:1]
	s_cmp_eq_u32 s100, 1
	s_cbranch_scc0 .Lp2_done
	s_mov_b32 s100, 2
	s_branch .Lp2_again
.Lp2_done:
	v_readlane_b32 s13, v255, 30
	s_add_i32 s8, s13, 5
	s_cmp_lt_i32 s8, s83
	s_cbranch_scc0 .LBB0_508
	s_waitcnt vmcnt(0)
	s_waitcnt vmcnt(0) lgkmcnt(0)
	s_barrier
	s_mov_b64 s[0:1], exec
	v_readlane_b32 s2, v254, 9
	v_readlane_b32 s3, v254, 10
	s_and_b64 s[2:3], s[0:1], s[2:3]
	s_mov_b64 exec, s[2:3]
	s_cbranch_execz .LBB0_507
	v_readlane_b32 s2, v255, 28
	s_waitcnt vmcnt(0) expcnt(0) lgkmcnt(0)
	s_nop 0
	v_mov_b32_e32 v0, s2
	ds_read_b32 v3, v0
	v_readlane_b32 s2, v255, 29
	s_waitcnt lgkmcnt(0)
	v_cmp_ne_u32_e32 vcc, 0, v3
	v_mov_b32_e32 v0, s2
	ds_read_b32 v2, v0
	s_cbranch_vccnz .LBB0_471
	s_mov_b32 s9, 1
	s_branch .LBB0_459

.Lepix_branch:
	s_branch .LBB0_521
	s_nop 0
	s_nop 0
.LBB0_520:
	s_waitcnt vmcnt(0)
	v_lshlrev_b32_e32 v68, 16, v62
	v_and_b32_e32 v69, 0xffff0000, v62
	v_lshlrev_b32_e32 v62, 16, v63
	v_and_b32_e32 v63, 0xffff0000, v63
	v_pk_mul_f32 v[68:69], v[174:175], v[68:69]
	v_lshlrev_b32_e32 v70, 16, v58
	v_and_b32_e32 v71, 0xffff0000, v58
	v_pk_mul_f32 v[62:63], v[174:175], v[62:63]
	v_lshlrev_b32_e32 v58, 16, v59
	v_and_b32_e32 v59, 0xffff0000, v59
	v_pk_fma_f32 v[30:31], v[30:31], v[70:71], v[68:69]
	v_pk_fma_f32 v[32:33], v[32:33], v[58:59], v[62:63]
	v_cvt_pk_bf16_f32 v30, v30, v31
	v_cvt_pk_bf16_f32 v31, v32, v33
	v_lshlrev_b32_e32 v32, 16, v64
	v_and_b32_e32 v33, 0xffff0000, v64
	v_pk_mul_f32 v[32:33], v[174:175], v[32:33]
	v_lshlrev_b32_e32 v58, 16, v60
	v_and_b32_e32 v59, 0xffff0000, v60
	v_pk_fma_f32 v[26:27], v[26:27], v[58:59], v[32:33]
	v_lshlrev_b32_e32 v58, 16, v61
	v_cvt_pk_bf16_f32 v32, v26, v27
	v_lshlrev_b32_e32 v26, 16, v65
	v_and_b32_e32 v27, 0xffff0000, v65
	v_pk_mul_f32 v[26:27], v[174:175], v[26:27]
	v_and_b32_e32 v59, 0xffff0000, v61
	v_pk_fma_f32 v[26:27], v[28:29], v[58:59], v[26:27]
	v_lshlrev_b32_e32 v28, 16, v46
	v_cvt_pk_bf16_f32 v33, v26, v27
	v_lshlrev_b32_e32 v26, 16, v50
	v_and_b32_e32 v27, 0xffff0000, v50
	v_pk_mul_f32 v[26:27], v[174:175], v[26:27]
	v_and_b32_e32 v29, 0xffff0000, v46
	v_pk_fma_f32 v[22:23], v[22:23], v[28:29], v[26:27]
	v_lshlrev_b32_e32 v26, 16, v51
	v_and_b32_e32 v27, 0xffff0000, v51
	v_pk_mul_f32 v[26:27], v[174:175], v[26:27]
	v_lshlrev_b32_e32 v28, 16, v47
	v_and_b32_e32 v29, 0xffff0000, v47
	v_pk_fma_f32 v[24:25], v[24:25], v[28:29], v[26:27]
	v_cvt_pk_bf16_f32 v22, v22, v23
	v_cvt_pk_bf16_f32 v23, v24, v25
	v_lshlrev_b32_e32 v24, 16, v52
	v_and_b32_e32 v25, 0xffff0000, v52
	v_pk_mul_f32 v[24:25], v[174:175], v[24:25]
	v_lshlrev_b32_e32 v26, 16, v48
	v_and_b32_e32 v27, 0xffff0000, v48
	v_add_u32_e32 v66, 0xa0, v170
	v_pk_fma_f32 v[18:19], v[18:19], v[26:27], v[24:25]
	v_ashrrev_i32_e32 v67, 31, v66
	v_cvt_pk_bf16_f32 v24, v18, v19
	v_lshlrev_b32_e32 v18, 16, v53
	v_and_b32_e32 v19, 0xffff0000, v53
	v_lshlrev_b64 v[66:67], 11, v[66:67]
	v_pk_mul_f32 v[18:19], v[174:175], v[18:19]
	v_lshlrev_b32_e32 v26, 16, v49
	v_and_b32_e32 v27, 0xffff0000, v49
	v_lshl_add_u64 v[66:67], s[0:1], 0, v[66:67]
	v_mov_b32_e32 v173, v1
	v_pk_fma_f32 v[18:19], v[20:21], v[26:27], v[18:19]
	v_lshl_add_u64 v[66:67], v[66:67], 0, v[172:173]
	v_cvt_pk_bf16_f32 v25, v18, v19
	v_lshlrev_b32_e32 v20, 16, v54
	v_and_b32_e32 v21, 0xffff0000, v54
	global_store_dwordx4 v[66:67], v[22:25], off offset:64
	v_pk_mul_f32 v[20:21], v[174:175], v[20:21]
	v_add_u32_e32 v18, 0xb0, v170
	v_lshlrev_b32_e32 v22, 16, v42
	v_and_b32_e32 v23, 0xffff0000, v42
	v_pk_fma_f32 v[14:15], v[14:15], v[22:23], v[20:21]
	v_lshlrev_b32_e32 v20, 16, v55
	v_and_b32_e32 v21, 0xffff0000, v55
	v_pk_mul_f32 v[20:21], v[174:175], v[20:21]
	v_lshlrev_b32_e32 v22, 16, v43
	v_and_b32_e32 v23, 0xffff0000, v43
	v_pk_fma_f32 v[16:17], v[16:17], v[22:23], v[20:21]
	v_cvt_pk_bf16_f32 v14, v14, v15
	v_cvt_pk_bf16_f32 v15, v16, v17
	v_lshlrev_b32_e32 v16, 16, v56
	v_and_b32_e32 v17, 0xffff0000, v56
	v_pk_mul_f32 v[16:17], v[174:175], v[16:17]
	v_lshlrev_b32_e32 v20, 16, v44
	v_and_b32_e32 v21, 0xffff0000, v44
	v_pk_fma_f32 v[10:11], v[10:11], v[20:21], v[16:17]
	v_lshlrev_b32_e32 v20, 16, v45
	v_cvt_pk_bf16_f32 v16, v10, v11
	v_lshlrev_b32_e32 v10, 16, v57
	v_and_b32_e32 v11, 0xffff0000, v57
	v_pk_mul_f32 v[10:11], v[174:175], v[10:11]
	v_and_b32_e32 v21, 0xffff0000, v45
	v_pk_fma_f32 v[10:11], v[12:13], v[20:21], v[10:11]
	v_lshlrev_b32_e32 v12, 16, v38
	v_cvt_pk_bf16_f32 v17, v10, v11
	v_lshlrev_b32_e32 v10, 16, v34
	v_and_b32_e32 v11, 0xffff0000, v34
	v_pk_mul_f32 v[10:11], v[174:175], v[10:11]
	v_and_b32_e32 v13, 0xffff0000, v38
	v_pk_fma_f32 v[6:7], v[6:7], v[12:13], v[10:11]
	v_lshlrev_b32_e32 v10, 16, v35
	v_and_b32_e32 v11, 0xffff0000, v35
	v_pk_mul_f32 v[10:11], v[174:175], v[10:11]
	v_lshlrev_b32_e32 v12, 16, v39
	v_and_b32_e32 v13, 0xffff0000, v39
	v_pk_fma_f32 v[8:9], v[8:9], v[12:13], v[10:11]
	v_cvt_pk_bf16_f32 v6, v6, v7
	v_cvt_pk_bf16_f32 v7, v8, v9
	v_lshlrev_b32_e32 v8, 16, v36
	v_and_b32_e32 v9, 0xffff0000, v36
	v_pk_mul_f32 v[8:9], v[174:175], v[8:9]
	v_lshlrev_b32_e32 v10, 16, v40
	v_and_b32_e32 v11, 0xffff0000, v40
	v_pk_fma_f32 v[2:3], v[2:3], v[10:11], v[8:9]
	v_ashrrev_i32_e32 v19, 31, v18
	v_cvt_pk_bf16_f32 v8, v2, v3
	v_lshlrev_b32_e32 v2, 16, v37
	v_and_b32_e32 v3, 0xffff0000, v37
	v_lshlrev_b64 v[18:19], 11, v[18:19]
	v_pk_mul_f32 v[2:3], v[174:175], v[2:3]
	v_lshlrev_b32_e32 v10, 16, v41
	v_and_b32_e32 v11, 0xffff0000, v41
	v_lshl_add_u64 v[18:19], s[0:1], 0, v[18:19]
	v_pk_fma_f32 v[2:3], v[4:5], v[10:11], v[2:3]
	v_lshl_add_u64 v[18:19], v[18:19], 0, v[172:173]
	v_cvt_pk_bf16_f32 v9, v2, v3
	s_and_b64 vcc, exec, s[36:37]
	s_mov_b32 s38, s68
	s_mov_b32 s2, s46
	s_mov_b64 s[90:91], s[88:89]
	s_mov_b64 s[62:63], s[84:85]
	global_store_dwordx4 v[66:67], v[30:33], off
	global_store_dwordx4 v[18:19], v[14:17], off
	global_store_dwordx4 v[18:19], v[6:9], off offset:64
	s_cbranch_vccnz .LBB0_545
